# S5 stage-3: Toeplitz k-loop unrolled 2x with alternating load register sets (counted vmcnt(6) instead of per-step vmcnt(0)), epilogue D and u loads hoisted with counted waits
# baseline (speedup 1.0000x reference)
; DI float lo2f(unsigned w) { return __uint_as_float(w << 16); }
; DI float hi2f(unsigned w) { return __uint_as_float(w & 0xffff0000u); }
; DI void st4(u16* p, float a, float b, float c, float d) { uint2 v; v.x = pack2(a, b); v.y = pack2(c, d); *reinterpret_cast<uint2*>(p) = v; }
; DI float geluf_(float x) { float u = 0.7978845608028654f * (x + 0.044715f * x * x * x); return x * sigmoidf_(2.0f * u); }
; DI void s5_stage3_item(const Params& P, int l, int it, u16* hs, int wave, int lane) {
;     ...
;     wgemm<4, 2>(acc, 4,
;                 [&](int i, int ks) { return ld8(W3 + ((size_t)(4 * jg + i) * 16 + jn) * 128 + ks * 32 + q * 8); },
;                 [&](int jt, int ks) { return *reinterpret_cast<const bf16x8*>(hs + (16 * (2 * th + jt) + jn) * HS_STRIDE + ks * 32 + q * 8); });
; #pragma unroll
;     for (int jt = 0; jt < 2; ++jt) {
;       const int n = 16 * (2 * th + jt) + jn;
; #pragma unroll
;       for (int i = 0; i < 4; ++i) {
;         const size_t tok = (size_t)b * S + n * 64 + 4 * jg + i;
;         uint2 uw = ld4(proj + tok * DINP + C_U + g * 16 + 4 * q);
;         const float y0 = acc[i][jt][0] + dsk[4 * q] * lo2f(uw.x), y1 = acc[i][jt][1] + dsk[4 * q + 1] * hi2f(uw.x);
;         const float y2 = acc[i][jt][2] + dsk[4 * q + 2] * lo2f(uw.y), y3 = acc[i][jt][3] + dsk[4 * q + 3] * hi2f(uw.y);
;         st4(yg + tok * 256 + g * 16 + 4 * q, geluf_(y0), geluf_(y1), geluf_(y2), geluf_(y3));
.LBB0_836:
	s_ashr_i32 s5, s4, 31
	s_ashr_i32 s3, s2, 31
	s_lshl_b64 s[4:5], s[4:5], 12
	s_ashr_i32 s7, s6, 31
	s_lshl_b64 s[10:11], s[2:3], 12
	v_lshl_add_u64 v[126:127], v[94:95], 0, s[4:5]
	s_lshl_b64 s[4:5], s[6:7], 12
	s_ashr_i32 s9, s8, 31
	v_lshl_add_u64 v[124:125], v[94:95], 0, s[10:11]
	v_lshl_add_u64 v[128:129], v[94:95], 0, s[4:5]
	s_lshl_b64 s[4:5], s[8:9], 12
	global_load_dwordx4 v[2:5], v[124:125], off
	global_load_dwordx4 v[6:9], v[124:125], off offset:64
	global_load_dwordx4 v[10:13], v[128:129], off
	global_load_dwordx4 v[34:37], v[128:129], off offset:64
	v_lshl_add_u64 v[134:135], v[94:95], 0, s[4:5]
	global_load_dwordx4 v[50:53], v[126:127], off
	global_load_dwordx4 v[54:57], v[124:125], off offset:128
	global_load_dwordx4 v[58:61], v[126:127], off offset:64
	global_load_dwordx4 v[62:65], v[126:127], off offset:128
	global_load_dwordx4 v[66:69], v[134:135], off
	global_load_dwordx4 v[70:73], v[128:129], off offset:128
	global_load_dwordx4 v[74:77], v[134:135], off offset:64
	global_load_dwordx4 v[78:81], v[134:135], off offset:128
	v_lshl_or_b32 v0, s16, 5, v162
	v_mul_u32_u24_e32 v82, 0x88, v0
	v_lshl_add_u32 v93, v82, 1, v92
	ds_read_b128 v[82:85], v93
	ds_read_b128 v[86:89], v93 offset:64
	ds_read_b128 v[108:111], v93 offset:4352
	ds_read_b128 v[112:115], v93 offset:128
	ds_read_b128 v[116:119], v93 offset:4416
	ds_read_b128 v[120:123], v93 offset:4480
	s_waitcnt vmcnt(11) lgkmcnt(5)
	v_mfma_f32_16x16x32_bf16 v[46:49], v[2:5], v[82:85], v[46:49]
	s_waitcnt lgkmcnt(3)
	v_mfma_f32_16x16x32_bf16 v[2:5], v[2:5], v[108:111], v[42:45]
	s_waitcnt vmcnt(7)
	v_mfma_f32_16x16x32_bf16 v[38:41], v[50:53], v[82:85], v[38:41]
	v_mfma_f32_16x16x32_bf16 v[30:33], v[50:53], v[108:111], v[30:33]
	v_mfma_f32_16x16x32_bf16 v[26:29], v[10:13], v[82:85], v[26:29]
	v_mfma_f32_16x16x32_bf16 v[10:13], v[10:13], v[108:111], v[22:25]
	s_waitcnt vmcnt(3)
	v_mfma_f32_16x16x32_bf16 v[18:21], v[66:69], v[82:85], v[18:21]
	v_mfma_f32_16x16x32_bf16 v[14:17], v[66:69], v[108:111], v[14:17]
	global_load_dwordx4 v[22:25], v[124:125], off offset:192
	global_load_dwordx4 v[42:45], v[126:127], off offset:192
	global_load_dwordx4 v[50:53], v[128:129], off offset:192
	global_load_dwordx4 v[66:69], v[134:135], off offset:192
	ds_read_b128 v[82:85], v93 offset:192
	ds_read_b128 v[108:111], v93 offset:4544
	v_mfma_f32_16x16x32_bf16 v[46:49], v[6:9], v[86:89], v[46:49]
	s_waitcnt lgkmcnt(3)
	v_mfma_f32_16x16x32_bf16 v[2:5], v[6:9], v[116:119], v[2:5]
	v_mfma_f32_16x16x32_bf16 v[6:9], v[58:61], v[86:89], v[38:41]
	v_mfma_f32_16x16x32_bf16 v[30:33], v[58:61], v[116:119], v[30:33]
	v_mfma_f32_16x16x32_bf16 v[26:29], v[34:37], v[86:89], v[26:29]
	v_mfma_f32_16x16x32_bf16 v[10:13], v[34:37], v[116:119], v[10:13]
	s_waitcnt vmcnt(5)
	v_mfma_f32_16x16x32_bf16 v[18:21], v[74:77], v[86:89], v[18:21]
	v_mfma_f32_16x16x32_bf16 v[14:17], v[74:77], v[116:119], v[14:17]
	v_mfma_f32_16x16x32_bf16 v[34:37], v[54:57], v[112:115], v[46:49]
	s_waitcnt lgkmcnt(2)
	v_mfma_f32_16x16x32_bf16 v[2:5], v[54:57], v[120:123], v[2:5]
	v_mfma_f32_16x16x32_bf16 v[6:9], v[62:65], v[112:115], v[6:9]
	v_mfma_f32_16x16x32_bf16 v[30:33], v[62:65], v[120:123], v[30:33]
	v_mfma_f32_16x16x32_bf16 v[38:41], v[70:73], v[112:115], v[26:29]
	v_mfma_f32_16x16x32_bf16 v[46:49], v[70:73], v[120:123], v[10:13]
	s_waitcnt vmcnt(4)
	v_mfma_f32_16x16x32_bf16 v[18:21], v[78:81], v[112:115], v[18:21]
	v_mfma_f32_16x16x32_bf16 v[54:57], v[78:81], v[120:123], v[14:17]
	s_waitcnt vmcnt(3) lgkmcnt(1)
	v_mfma_f32_16x16x32_bf16 v[58:61], v[22:25], v[82:85], v[34:37]
	s_waitcnt lgkmcnt(0)
	v_mfma_f32_16x16x32_bf16 v[14:17], v[22:25], v[108:111], v[2:5]
	s_waitcnt vmcnt(2)
	v_mfma_f32_16x16x32_bf16 v[26:29], v[42:45], v[82:85], v[6:9]
	v_mfma_f32_16x16x32_bf16 v[10:13], v[42:45], v[108:111], v[30:33]
	s_waitcnt vmcnt(1)
	v_mfma_f32_16x16x32_bf16 v[22:25], v[50:53], v[82:85], v[38:41]
	v_mfma_f32_16x16x32_bf16 v[6:9], v[50:53], v[108:111], v[46:49]
	s_waitcnt vmcnt(0)
	v_mfma_f32_16x16x32_bf16 v[18:21], v[66:69], v[82:85], v[18:21]
	v_mfma_f32_16x16x32_bf16 v[2:5], v[66:69], v[108:111], v[54:57]
	s_add_u32 s2, s0, s2
	s_addc_u32 s3, s1, s3
	v_lshlrev_b32_e32 v0, 6, v0
	v_lshl_add_u64 v[32:33], s[2:3], 0, v[0:1]
	v_mov_b64_e32 v[30:31], s[76:77]
	v_mad_u64_u32 v[34:35], s[4:5], v32, s45, v[30:31]
	v_mad_i32_i24 v35, v33, s45, v35
	v_lshl_add_u64 v[34:35], v[34:35], 0, s[34:35]
	v_mov_b32_e32 v105, v1
	v_lshl_add_u64 v[34:35], v[34:35], 0, v[104:105]
	global_load_dwordx4 v[236:239], v[96:97], off
	global_load_dwordx2 v[36:37], v[34:35], off offset:2384
	v_add_co_u32_e32 v240, vcc, s63, v34
	s_nop 1
	v_addc_co_u32_e32 v241, vcc, 0, v35, vcc
	global_load_dwordx2 v[240:241], v[240:241], off offset:3408
	v_add_co_u32_e32 v242, vcc, s25, v34
	s_nop 1
	v_addc_co_u32_e32 v243, vcc, 0, v35, vcc
	global_load_dwordx2 v[242:243], v[242:243], off offset:336
	v_add_co_u32_e32 v244, vcc, s42, v34
	s_nop 1
	v_addc_co_u32_e32 v245, vcc, 0, v35, vcc
	global_load_dwordx2 v[244:245], v[244:245], off offset:1360
	v_lshlrev_b64 v[32:33], 9, v[32:33]
	v_lshl_add_u64 v[44:45], v[98:99], 0, v[32:33]
	v_or_b32_e32 v0, 0x400, v0
	s_add_i32 s15, s15, 1
	s_add_i32 s14, s14, 2
	s_cmp_lg_u32 s15, 8
	s_waitcnt vmcnt(3)
; DI float lo2f(unsigned w) { return __uint_as_float(w << 16); }
; DI float hi2f(unsigned w) { return __uint_as_float(w & 0xffff0000u); }
; DI void st4(u16* p, float a, float b, float c, float d) { uint2 v; v.x = pack2(a, b); v.y = pack2(c, d); *reinterpret_cast<uint2*>(p) = v; }
; DI float geluf_(float x) { float u = 0.7978845608028654f * (x + 0.044715f * x * x * x); return x * sigmoidf_(2.0f * u); }
; DI void s5_stage3_item(const Params& P, int l, int it, u16* hs, int wave, int lane) {
;     ...
; #pragma unroll
;     for (int jt = 0; jt < 2; ++jt) {
;       const int n = 16 * (2 * th + jt) + jn;
; #pragma unroll
;       for (int i = 0; i < 4; ++i) {
;         const size_t tok = (size_t)b * S + n * 64 + 4 * jg + i;
;         uint2 uw = ld4(proj + tok * DINP + C_U + g * 16 + 4 * q);
;         const float y0 = acc[i][jt][0] + dsk[4 * q] * lo2f(uw.x), y1 = acc[i][jt][1] + dsk[4 * q + 1] * hi2f(uw.x);
;         const float y2 = acc[i][jt][2] + dsk[4 * q + 2] * lo2f(uw.y), y3 = acc[i][jt][3] + dsk[4 * q + 3] * hi2f(uw.y);
;         st4(yg + tok * 256 + g * 16 + 4 * q, geluf_(y0), geluf_(y1), geluf_(y2), geluf_(y3));
	v_lshlrev_b32_e32 v40, 16, v36
	v_and_b32_e32 v41, 0xffff0000, v36
	v_lshlrev_b32_e32 v42, 16, v37
	v_and_b32_e32 v43, 0xffff0000, v37
	v_pk_fma_f32 v[36:37], v[236:237], v[40:41], v[58:59]
	s_nop 0
	v_mul_f32_e32 v40, 0x3d372713, v36
	v_mul_f32_e32 v41, 0x3d372713, v37
	v_mul_f32_e32 v40, v36, v40
	v_mul_f32_e32 v41, v37, v41
	v_fma_f32 v40, v36, v40, v36
	v_fma_f32 v41, v37, v41, v37
	v_mul_f32_e32 v40, 0x3f4c422a, v40
	v_mul_f32_e32 v41, 0x3f4c422a, v41
	v_add_f32_e32 v40, v40, v40
	v_add_f32_e32 v41, v41, v41
	v_mul_f32_e32 v40, 0xbfb8aa3b, v40
	v_mul_f32_e32 v41, 0xbfb8aa3b, v41
	v_exp_f32_e32 v40, v40
	v_exp_f32_e32 v41, v41
	v_pk_fma_f32 v[38:39], v[238:239], v[42:43], v[60:61]
	v_add_f32_e32 v40, 1.0, v40
	v_add_f32_e32 v41, 1.0, v41
	v_rcp_f32_e32 v40, v40
	v_rcp_f32_e32 v41, v41
	s_nop 0
	v_pk_mul_f32 v[36:37], v[36:37], v[40:41]
	v_mul_f32_e32 v40, 0x3d372713, v38
	v_mul_f32_e32 v41, 0x3d372713, v39
	v_mul_f32_e32 v40, v38, v40
	v_mul_f32_e32 v41, v39, v41
	v_fma_f32 v40, v38, v40, v38
	v_fma_f32 v41, v39, v41, v39
	v_mul_f32_e32 v40, 0x3f4c422a, v40
	v_mul_f32_e32 v41, 0x3f4c422a, v41
	v_add_f32_e32 v40, v40, v40
	v_add_f32_e32 v41, v41, v41
	v_mul_f32_e32 v40, 0xbfb8aa3b, v40
	v_mul_f32_e32 v41, 0xbfb8aa3b, v41
	v_exp_f32_e32 v40, v40
	v_exp_f32_e32 v41, v41
	v_cvt_pk_bf16_f32 v36, v36, v37
	v_add_f32_e32 v40, 1.0, v40
	v_add_f32_e32 v41, 1.0, v41
	v_rcp_f32_e32 v40, v40
	v_rcp_f32_e32 v41, v41
	s_nop 0
	v_pk_mul_f32 v[38:39], v[38:39], v[40:41]
	s_nop 0
	v_cvt_pk_bf16_f32 v37, v38, v39
	global_store_dwordx2 v[44:45], v[36:37], off
	s_waitcnt vmcnt(3)
	v_lshlrev_b32_e32 v40, 16, v240
	v_and_b32_e32 v41, 0xffff0000, v240
	v_lshlrev_b32_e32 v42, 16, v241
	v_and_b32_e32 v43, 0xffff0000, v241
	v_or_b32_e32 v36, 0x200, v32
	v_mov_b32_e32 v37, v33
	v_lshl_add_u64 v[44:45], v[98:99], 0, v[36:37]
	v_pk_fma_f32 v[26:27], v[236:237], v[40:41], v[26:27]
	s_nop 0
	v_mul_f32_e32 v36, 0x3d372713, v26
	v_mul_f32_e32 v37, 0x3d372713, v27
	v_mul_f32_e32 v36, v26, v36
	v_mul_f32_e32 v37, v27, v37
	v_fma_f32 v36, v26, v36, v26
	v_fma_f32 v37, v27, v37, v27
	v_mul_f32_e32 v36, 0x3f4c422a, v36
	v_mul_f32_e32 v37, 0x3f4c422a, v37
	v_add_f32_e32 v36, v36, v36
	v_add_f32_e32 v37, v37, v37
	v_mul_f32_e32 v36, 0xbfb8aa3b, v36
	v_mul_f32_e32 v37, 0xbfb8aa3b, v37
	v_exp_f32_e32 v36, v36
	v_exp_f32_e32 v37, v37
	v_pk_fma_f32 v[28:29], v[238:239], v[42:43], v[28:29]
	v_add_f32_e32 v36, 1.0, v36
	v_add_f32_e32 v37, 1.0, v37
	v_rcp_f32_e32 v36, v36
	v_rcp_f32_e32 v37, v37
	s_nop 0
	v_pk_mul_f32 v[26:27], v[26:27], v[36:37]
	v_mul_f32_e32 v36, 0x3d372713, v28
	v_mul_f32_e32 v37, 0x3d372713, v29
	v_mul_f32_e32 v36, v28, v36
	v_mul_f32_e32 v37, v29, v37
	v_fma_f32 v36, v28, v36, v28
	v_fma_f32 v37, v29, v37, v29
	v_mul_f32_e32 v36, 0x3f4c422a, v36
	v_mul_f32_e32 v37, 0x3f4c422a, v37
	v_add_f32_e32 v36, v36, v36
	v_add_f32_e32 v37, v37, v37
	v_mul_f32_e32 v36, 0xbfb8aa3b, v36
	v_mul_f32_e32 v37, 0xbfb8aa3b, v37
	v_exp_f32_e32 v36, v36
	v_exp_f32_e32 v37, v37
	v_cvt_pk_bf16_f32 v26, v26, v27
	v_add_f32_e32 v36, 1.0, v36
	v_add_f32_e32 v37, 1.0, v37
	v_rcp_f32_e32 v36, v36
	v_rcp_f32_e32 v37, v37
	s_nop 0
	v_pk_mul_f32 v[28:29], v[28:29], v[36:37]
	s_nop 0
	v_cvt_pk_bf16_f32 v27, v28, v29
	global_store_dwordx2 v[44:45], v[26:27], off
	s_waitcnt vmcnt(3)
	v_lshlrev_b32_e32 v36, 16, v242
	v_and_b32_e32 v37, 0xffff0000, v242
	v_lshlrev_b32_e32 v38, 16, v243
	v_and_b32_e32 v39, 0xffff0000, v243
	v_or_b32_e32 v26, 0x400, v32
	v_mov_b32_e32 v27, v33
	v_lshl_add_u64 v[40:41], v[98:99], 0, v[26:27]
	v_or_b32_e32 v32, 0x600, v32
	v_pk_fma_f32 v[22:23], v[236:237], v[36:37], v[22:23]
	s_nop 0
	v_mul_f32_e32 v26, 0x3d372713, v22
	v_mul_f32_e32 v27, 0x3d372713, v23
	v_mul_f32_e32 v26, v22, v26
	v_mul_f32_e32 v27, v23, v27
	v_fma_f32 v26, v22, v26, v22
	v_fma_f32 v27, v23, v27, v23
	v_mul_f32_e32 v26, 0x3f4c422a, v26
	v_mul_f32_e32 v27, 0x3f4c422a, v27
	v_add_f32_e32 v26, v26, v26
	v_add_f32_e32 v27, v27, v27
	v_mul_f32_e32 v26, 0xbfb8aa3b, v26
	v_mul_f32_e32 v27, 0xbfb8aa3b, v27
	v_exp_f32_e32 v26, v26
	v_exp_f32_e32 v27, v27
	v_pk_fma_f32 v[24:25], v[238:239], v[38:39], v[24:25]
	v_add_f32_e32 v26, 1.0, v26
	v_add_f32_e32 v27, 1.0, v27
	v_rcp_f32_e32 v26, v26
	v_rcp_f32_e32 v27, v27
	s_nop 0
	v_pk_mul_f32 v[22:23], v[22:23], v[26:27]
	v_mul_f32_e32 v26, 0x3d372713, v24
	v_mul_f32_e32 v27, 0x3d372713, v25
	v_mul_f32_e32 v26, v24, v26
	v_mul_f32_e32 v27, v25, v27
	v_fma_f32 v26, v24, v26, v24
	v_fma_f32 v27, v25, v27, v25
	v_mul_f32_e32 v26, 0x3f4c422a, v26
	v_mul_f32_e32 v27, 0x3f4c422a, v27
	v_add_f32_e32 v26, v26, v26
	v_add_f32_e32 v27, v27, v27
	v_mul_f32_e32 v26, 0xbfb8aa3b, v26
	v_mul_f32_e32 v27, 0xbfb8aa3b, v27
	v_exp_f32_e32 v26, v26
	v_exp_f32_e32 v27, v27
	v_cvt_pk_bf16_f32 v22, v22, v23
	v_add_f32_e32 v26, 1.0, v26
	v_add_f32_e32 v27, 1.0, v27
	v_rcp_f32_e32 v26, v26
	v_rcp_f32_e32 v27, v27
	s_nop 0
	v_pk_mul_f32 v[24:25], v[24:25], v[26:27]
	s_nop 0
	v_cvt_pk_bf16_f32 v23, v24, v25
	global_store_dwordx2 v[40:41], v[22:23], off
	s_waitcnt vmcnt(3)
; DI float lo2f(unsigned w) { return __uint_as_float(w << 16); }
; DI float hi2f(unsigned w) { return __uint_as_float(w & 0xffff0000u); }
; DI void st4(u16* p, float a, float b, float c, float d) { uint2 v; v.x = pack2(a, b); v.y = pack2(c, d); *reinterpret_cast<uint2*>(p) = v; }
; DI float geluf_(float x) { float u = 0.7978845608028654f * (x + 0.044715f * x * x * x); return x * sigmoidf_(2.0f * u); }
; DI void s5_stage3_item(const Params& P, int l, int it, u16* hs, int wave, int lane) {
;     ...
; #pragma unroll
;     for (int jt = 0; jt < 2; ++jt) {
;       const int n = 16 * (2 * th + jt) + jn;
; #pragma unroll
;       for (int i = 0; i < 4; ++i) {
;         const size_t tok = (size_t)b * S + n * 64 + 4 * jg + i;
;         uint2 uw = ld4(proj + tok * DINP + C_U + g * 16 + 4 * q);
;         const float y0 = acc[i][jt][0] + dsk[4 * q] * lo2f(uw.x), y1 = acc[i][jt][1] + dsk[4 * q + 1] * hi2f(uw.x);
;         const float y2 = acc[i][jt][2] + dsk[4 * q + 2] * lo2f(uw.y), y3 = acc[i][jt][3] + dsk[4 * q + 3] * hi2f(uw.y);
;         st4(yg + tok * 256 + g * 16 + 4 * q, geluf_(y0), geluf_(y1), geluf_(y2), geluf_(y3));
	v_lshlrev_b32_e32 v26, 16, v244
	v_and_b32_e32 v27, 0xffff0000, v244
	v_lshlrev_b32_e32 v24, 16, v245
	v_and_b32_e32 v25, 0xffff0000, v245
	v_lshl_add_u64 v[22:23], v[98:99], 0, v[32:33]
	v_pk_fma_f32 v[18:19], v[236:237], v[26:27], v[18:19]
	v_pk_fma_f32 v[20:21], v[238:239], v[24:25], v[20:21]
	v_mul_f32_e32 v26, 0x3d372713, v18
	v_mul_f32_e32 v27, 0x3d372713, v19
	v_mul_f32_e32 v24, 0x3d372713, v20
	v_mul_f32_e32 v25, 0x3d372713, v21
	v_mul_f32_e32 v26, v18, v26
	v_mul_f32_e32 v27, v19, v27
	v_mul_f32_e32 v24, v20, v24
	v_mul_f32_e32 v25, v21, v25
	v_fma_f32 v26, v18, v26, v18
	v_fma_f32 v27, v19, v27, v19
	v_fma_f32 v24, v20, v24, v20
	v_fma_f32 v25, v21, v25, v21
	v_mul_f32_e32 v26, 0x3f4c422a, v26
	v_mul_f32_e32 v27, 0x3f4c422a, v27
	v_mul_f32_e32 v24, 0x3f4c422a, v24
	v_mul_f32_e32 v25, 0x3f4c422a, v25
	v_add_f32_e32 v26, v26, v26
	v_add_f32_e32 v27, v27, v27
	v_add_f32_e32 v24, v24, v24
	v_add_f32_e32 v25, v25, v25
	v_mul_f32_e32 v26, 0xbfb8aa3b, v26
	v_mul_f32_e32 v27, 0xbfb8aa3b, v27
	v_mul_f32_e32 v24, 0xbfb8aa3b, v24
	v_mul_f32_e32 v25, 0xbfb8aa3b, v25
	v_exp_f32_e32 v26, v26
	v_exp_f32_e32 v27, v27
	v_exp_f32_e32 v24, v24
	v_exp_f32_e32 v25, v25
	v_add_f32_e32 v26, 1.0, v26
	v_add_f32_e32 v27, 1.0, v27
	v_add_f32_e32 v24, 1.0, v24
	v_add_f32_e32 v25, 1.0, v25
	v_rcp_f32_e32 v26, v26
	v_rcp_f32_e32 v27, v27
	v_rcp_f32_e32 v24, v24
	v_rcp_f32_e32 v25, v25
	v_pk_mul_f32 v[18:19], v[18:19], v[26:27]
	s_nop 0
	v_cvt_pk_bf16_f32 v18, v18, v19
	v_pk_mul_f32 v[20:21], v[20:21], v[24:25]
	s_nop 0
	v_cvt_pk_bf16_f32 v19, v20, v21
	global_store_dwordx2 v[22:23], v[18:19], off
	v_lshl_add_u64 v[18:19], s[2:3], 0, v[0:1]
	v_mad_u64_u32 v[20:21], s[2:3], v18, s45, v[30:31]
	v_mad_i32_i24 v21, v19, s45, v21
	v_lshl_add_u64 v[20:21], v[20:21], 0, s[34:35]
	v_lshl_add_u64 v[20:21], v[20:21], 0, v[104:105]
	global_load_dwordx2 v[22:23], v[20:21], off offset:2384
	v_add_co_u32_e32 v240, vcc, s63, v20
	s_nop 1
	v_addc_co_u32_e32 v241, vcc, 0, v21, vcc
	global_load_dwordx2 v[240:241], v[240:241], off offset:3408
	v_add_co_u32_e32 v242, vcc, s25, v20
	s_nop 1
	v_addc_co_u32_e32 v243, vcc, 0, v21, vcc
	global_load_dwordx2 v[242:243], v[242:243], off offset:336
	v_add_co_u32_e32 v244, vcc, s42, v20
	s_nop 1
	v_addc_co_u32_e32 v245, vcc, 0, v21, vcc
	global_load_dwordx2 v[244:245], v[244:245], off offset:1360
	v_lshlrev_b64 v[18:19], 9, v[18:19]
	v_lshl_add_u64 v[30:31], v[98:99], 0, v[18:19]
	s_waitcnt vmcnt(3)
	v_lshlrev_b32_e32 v26, 16, v22
	v_and_b32_e32 v27, 0xffff0000, v22
	v_lshlrev_b32_e32 v28, 16, v23
	v_and_b32_e32 v29, 0xffff0000, v23
	v_pk_fma_f32 v[14:15], v[236:237], v[26:27], v[14:15]
	s_nop 0
	v_mul_f32_e32 v0, 0x3d372713, v14
	v_mul_f32_e32 v0, v14, v0
	v_fma_f32 v0, v14, v0, v14
	v_mul_f32_e32 v0, 0x3f4c422a, v0
	v_add_f32_e32 v0, v0, v0
	v_mul_f32_e32 v0, 0xbfb8aa3b, v0
	v_exp_f32_e32 v0, v0
	v_pk_fma_f32 v[16:17], v[238:239], v[28:29], v[16:17]
	v_add_f32_e32 v0, 1.0, v0
	v_rcp_f32_e32 v22, v0
	v_mul_f32_e32 v0, 0x3d372713, v15
	v_mul_f32_e32 v0, v15, v0
	v_fma_f32 v0, v15, v0, v15
	v_mul_f32_e32 v0, 0x3f4c422a, v0
	v_add_f32_e32 v0, v0, v0
	v_mul_f32_e32 v0, 0xbfb8aa3b, v0
	v_exp_f32_e32 v0, v0
	s_nop 0
	v_add_f32_e32 v0, 1.0, v0
	v_rcp_f32_e32 v23, v0
	v_mul_f32_e32 v0, 0x3d372713, v16
	v_mul_f32_e32 v0, v16, v0
	v_fma_f32 v0, v16, v0, v16
	v_mul_f32_e32 v0, 0x3f4c422a, v0
	v_add_f32_e32 v0, v0, v0
	v_mul_f32_e32 v0, 0xbfb8aa3b, v0
	v_exp_f32_e32 v0, v0
	v_pk_mul_f32 v[14:15], v[14:15], v[22:23]
	v_add_f32_e32 v0, 1.0, v0
	v_rcp_f32_e32 v22, v0
	v_mul_f32_e32 v0, 0x3d372713, v17
	v_mul_f32_e32 v0, v17, v0
	v_fma_f32 v0, v17, v0, v17
	v_mul_f32_e32 v0, 0x3f4c422a, v0
	v_add_f32_e32 v0, v0, v0
	v_mul_f32_e32 v0, 0xbfb8aa3b, v0
	v_exp_f32_e32 v0, v0
	v_cvt_pk_bf16_f32 v14, v14, v15
	v_add_f32_e32 v0, 1.0, v0
	v_rcp_f32_e32 v23, v0
	s_nop 0
	v_pk_mul_f32 v[16:17], v[16:17], v[22:23]
	s_nop 0
	v_cvt_pk_bf16_f32 v15, v16, v17
	global_store_dwordx2 v[30:31], v[14:15], off
	s_waitcnt vmcnt(3)
; DI float lo2f(unsigned w) { return __uint_as_float(w << 16); }
; DI float hi2f(unsigned w) { return __uint_as_float(w & 0xffff0000u); }
; DI void st4(u16* p, float a, float b, float c, float d) { uint2 v; v.x = pack2(a, b); v.y = pack2(c, d); *reinterpret_cast<uint2*>(p) = v; }
; DI float geluf_(float x) { float u = 0.7978845608028654f * (x + 0.044715f * x * x * x); return x * sigmoidf_(2.0f * u); }
; DI void s5_stage3_item(const Params& P, int l, int it, u16* hs, int wave, int lane) {
;     ...
; #pragma unroll
;     for (int jt = 0; jt < 2; ++jt) {
;       const int n = 16 * (2 * th + jt) + jn;
; #pragma unroll
;       for (int i = 0; i < 4; ++i) {
;         const size_t tok = (size_t)b * S + n * 64 + 4 * jg + i;
;         uint2 uw = ld4(proj + tok * DINP + C_U + g * 16 + 4 * q);
;         const float y0 = acc[i][jt][0] + dsk[4 * q] * lo2f(uw.x), y1 = acc[i][jt][1] + dsk[4 * q + 1] * hi2f(uw.x);
;         const float y2 = acc[i][jt][2] + dsk[4 * q + 2] * lo2f(uw.y), y3 = acc[i][jt][3] + dsk[4 * q + 3] * hi2f(uw.y);
;         st4(yg + tok * 256 + g * 16 + 4 * q, geluf_(y0), geluf_(y1), geluf_(y2), geluf_(y3));
;       }
;     }
;   }
	v_lshlrev_b32_e32 v22, 16, v240
	v_and_b32_e32 v23, 0xffff0000, v240
	v_lshlrev_b32_e32 v24, 16, v241
	v_and_b32_e32 v25, 0xffff0000, v241
	v_or_b32_e32 v14, 0x200, v18
	v_mov_b32_e32 v15, v19
	v_lshl_add_u64 v[26:27], v[98:99], 0, v[14:15]
	v_pk_fma_f32 v[10:11], v[236:237], v[22:23], v[10:11]
	s_nop 0
	v_mul_f32_e32 v0, 0x3d372713, v10
	v_mul_f32_e32 v0, v10, v0
	v_fma_f32 v0, v10, v0, v10
	v_mul_f32_e32 v0, 0x3f4c422a, v0
	v_add_f32_e32 v0, v0, v0
	v_mul_f32_e32 v0, 0xbfb8aa3b, v0
	v_exp_f32_e32 v0, v0
	v_pk_fma_f32 v[12:13], v[238:239], v[24:25], v[12:13]
	v_add_f32_e32 v0, 1.0, v0
	v_rcp_f32_e32 v14, v0
	v_mul_f32_e32 v0, 0x3d372713, v11
	v_mul_f32_e32 v0, v11, v0
	v_fma_f32 v0, v11, v0, v11
	v_mul_f32_e32 v0, 0x3f4c422a, v0
	v_add_f32_e32 v0, v0, v0
	v_mul_f32_e32 v0, 0xbfb8aa3b, v0
	v_exp_f32_e32 v0, v0
	s_nop 0
	v_add_f32_e32 v0, 1.0, v0
	v_rcp_f32_e32 v15, v0
	v_mul_f32_e32 v0, 0x3d372713, v12
	v_mul_f32_e32 v0, v12, v0
	v_fma_f32 v0, v12, v0, v12
	v_mul_f32_e32 v0, 0x3f4c422a, v0
	v_add_f32_e32 v0, v0, v0
	v_mul_f32_e32 v0, 0xbfb8aa3b, v0
	v_exp_f32_e32 v0, v0
	v_pk_mul_f32 v[10:11], v[10:11], v[14:15]
	v_add_f32_e32 v0, 1.0, v0
	v_rcp_f32_e32 v14, v0
	v_mul_f32_e32 v0, 0x3d372713, v13
	v_mul_f32_e32 v0, v13, v0
	v_fma_f32 v0, v13, v0, v13
	v_mul_f32_e32 v0, 0x3f4c422a, v0
	v_add_f32_e32 v0, v0, v0
	v_mul_f32_e32 v0, 0xbfb8aa3b, v0
	v_exp_f32_e32 v0, v0
	v_cvt_pk_bf16_f32 v10, v10, v11
	v_add_f32_e32 v0, 1.0, v0
	v_rcp_f32_e32 v15, v0
	s_nop 0
	v_pk_mul_f32 v[12:13], v[12:13], v[14:15]
	s_nop 0
	v_cvt_pk_bf16_f32 v11, v12, v13
	global_store_dwordx2 v[26:27], v[10:11], off
	s_waitcnt vmcnt(3)
	v_lshlrev_b32_e32 v14, 16, v242
	v_and_b32_e32 v15, 0xffff0000, v242
	v_lshlrev_b32_e32 v16, 16, v243
	v_and_b32_e32 v17, 0xffff0000, v243
	v_or_b32_e32 v10, 0x400, v18
	v_mov_b32_e32 v11, v19
	v_lshl_add_u64 v[22:23], v[98:99], 0, v[10:11]
	v_or_b32_e32 v18, 0x600, v18
	v_pk_fma_f32 v[6:7], v[236:237], v[14:15], v[6:7]
	s_nop 0
	v_mul_f32_e32 v0, 0x3d372713, v6
	v_mul_f32_e32 v0, v6, v0
	v_fma_f32 v0, v6, v0, v6
	v_mul_f32_e32 v0, 0x3f4c422a, v0
	v_add_f32_e32 v0, v0, v0
	v_mul_f32_e32 v0, 0xbfb8aa3b, v0
	v_exp_f32_e32 v0, v0
	v_pk_fma_f32 v[8:9], v[238:239], v[16:17], v[8:9]
	v_add_f32_e32 v0, 1.0, v0
	v_rcp_f32_e32 v10, v0
	v_mul_f32_e32 v0, 0x3d372713, v7
	v_mul_f32_e32 v0, v7, v0
	v_fma_f32 v0, v7, v0, v7
	v_mul_f32_e32 v0, 0x3f4c422a, v0
	v_add_f32_e32 v0, v0, v0
	v_mul_f32_e32 v0, 0xbfb8aa3b, v0
	v_exp_f32_e32 v0, v0
	s_nop 0
	v_add_f32_e32 v0, 1.0, v0
	v_rcp_f32_e32 v11, v0
	v_mul_f32_e32 v0, 0x3d372713, v8
	v_mul_f32_e32 v0, v8, v0
	v_fma_f32 v0, v8, v0, v8
	v_mul_f32_e32 v0, 0x3f4c422a, v0
	v_add_f32_e32 v0, v0, v0
	v_mul_f32_e32 v0, 0xbfb8aa3b, v0
	v_exp_f32_e32 v0, v0
	v_pk_mul_f32 v[6:7], v[6:7], v[10:11]
	v_add_f32_e32 v0, 1.0, v0
	v_rcp_f32_e32 v10, v0
	v_mul_f32_e32 v0, 0x3d372713, v9
	v_mul_f32_e32 v0, v9, v0
	v_fma_f32 v0, v9, v0, v9
	v_mul_f32_e32 v0, 0x3f4c422a, v0
	v_add_f32_e32 v0, v0, v0
	v_mul_f32_e32 v0, 0xbfb8aa3b, v0
	v_exp_f32_e32 v0, v0
	v_cvt_pk_bf16_f32 v6, v6, v7
	v_add_f32_e32 v0, 1.0, v0
	v_rcp_f32_e32 v11, v0
	s_nop 0
	v_pk_mul_f32 v[8:9], v[8:9], v[10:11]
	s_nop 0
	v_cvt_pk_bf16_f32 v7, v8, v9
	global_store_dwordx2 v[22:23], v[6:7], off
	s_waitcnt vmcnt(3)
	v_lshlrev_b32_e32 v10, 16, v244
	v_and_b32_e32 v11, 0xffff0000, v244
	v_pk_fma_f32 v[2:3], v[236:237], v[10:11], v[2:3]
	v_lshlrev_b32_e32 v8, 16, v245
	v_mul_f32_e32 v0, 0x3d372713, v2
	v_mul_f32_e32 v0, v2, v0
	v_fma_f32 v0, v2, v0, v2
	v_mul_f32_e32 v0, 0x3f4c422a, v0
	v_add_f32_e32 v0, v0, v0
	v_mul_f32_e32 v0, 0xbfb8aa3b, v0
	v_exp_f32_e32 v0, v0
	v_and_b32_e32 v9, 0xffff0000, v245
	v_pk_fma_f32 v[4:5], v[238:239], v[8:9], v[4:5]
	v_lshl_add_u64 v[6:7], v[98:99], 0, v[18:19]
	v_add_f32_e32 v0, 1.0, v0
	v_rcp_f32_e32 v10, v0
	v_mul_f32_e32 v0, 0x3d372713, v3
	v_mul_f32_e32 v0, v3, v0
	v_fma_f32 v0, v3, v0, v3
	v_mul_f32_e32 v0, 0x3f4c422a, v0
	v_add_f32_e32 v0, v0, v0
	v_mul_f32_e32 v0, 0xbfb8aa3b, v0
	v_exp_f32_e32 v0, v0
	s_nop 0
	v_add_f32_e32 v0, 1.0, v0
	v_rcp_f32_e32 v11, v0
	v_mul_f32_e32 v0, 0x3d372713, v4
	v_mul_f32_e32 v0, v4, v0
	v_fma_f32 v0, v4, v0, v4
	v_mul_f32_e32 v0, 0x3f4c422a, v0
	v_add_f32_e32 v0, v0, v0
	v_mul_f32_e32 v0, 0xbfb8aa3b, v0
	v_exp_f32_e32 v0, v0
	v_pk_mul_f32 v[2:3], v[2:3], v[10:11]
	v_add_f32_e32 v0, 1.0, v0
	v_rcp_f32_e32 v8, v0
	v_mul_f32_e32 v0, 0x3d372713, v5
	v_mul_f32_e32 v0, v5, v0
	v_fma_f32 v0, v5, v0, v5
	v_mul_f32_e32 v0, 0x3f4c422a, v0
	v_add_f32_e32 v0, v0, v0
	v_mul_f32_e32 v0, 0xbfb8aa3b, v0
	v_exp_f32_e32 v0, v0
	v_cvt_pk_bf16_f32 v2, v2, v3
	v_add_f32_e32 v0, 1.0, v0
	v_rcp_f32_e32 v9, v0
	s_nop 0
	v_pk_mul_f32 v[4:5], v[4:5], v[8:9]
	s_nop 0
	v_cvt_pk_bf16_f32 v3, v4, v5
	global_store_dwordx2 v[6:7], v[2:3], off
	s_cbranch_scc0 .LBB0_793

; template <int AT, int BT, class FA, class FB>
; DI void wgemm(f32x4 (&acc)[AT][BT], int ksteps, FA fa, FB fb) {
;   bf16x8 a0[AT], b0[BT], a1[AT], b1[BT];
;   const int k1 = (ksteps > 1) ? 1 : 0;
; #pragma unroll
;   for (int i = 0; i < AT; ++i) { a0[i] = fa(i, 0); a1[i] = fa(i, k1); }
; #pragma unroll
;   for (int j = 0; j < BT; ++j) { b0[j] = fb(j, 0); b1[j] = fb(j, k1); }
;   for (int ks = 0; ks < ksteps; ++ks) {
;     bf16x8 a2[AT], b2[BT];
;     const int kn = (ks + 2 < ksteps) ? ks + 2 : ksteps - 1;
; #pragma unroll
;     for (int i = 0; i < AT; ++i) a2[i] = fa(i, kn);
; #pragma unroll
;     for (int j = 0; j < BT; ++j) b2[j] = fb(j, kn);
; DI void s5_stage3_item(const Params& P, int l, int it, u16* hs, int wave, int lane) {
;     ...
;   for (int gi = 0; gi < 8; ++gi) {
;     const int jg = wave + 4 * (gi >> 1);
;     const int th = gi & 1;
;     f32x4 acc[4][2]; zero_acc(acc);
;     wgemm<4, 2>(acc, 2 * jg + 2,
;                 [&](int i, int ks) { const int j = 4 * jg + i, ii = 2 * ks + (q >> 1); const int d = j - ii;
;                                      return (d >= 0) ? ld8(Kt + ((size_t)d * 16 + jn) * 16 + (q & 1) * 8) : zf; },
;                 [&](int jt, int ks) { return ld8(up + ((size_t)(2 * th + jt) * 16 * 64 + 2 * ks) * DINP); });
.LBB0_853:
	s_or_b64 exec, exec, s[10:11]
	s_and_b32 s16, s15, 1
	s_cmp_lt_i32 s17, 0
	s_cbranch_scc1 .LBB0_835
	s_lshl_b32 s3, s16, 1
	s_or_b32 s5, s3, 1
	s_mul_i32 s10, s5, 0x500000
	s_mov_b32 s11, s35
	v_lshl_add_u64 v[14:15], v[90:91], 0, s[10:11]
	v_add_co_u32_e32 v16, vcc, 0x3000, v14
	s_mul_i32 s10, s16, 0xa00000
	s_nop 0
	v_addc_co_u32_e32 v17, vcc, 0, v15, vcc
	v_lshl_add_u64 v[18:19], v[90:91], 0, s[10:11]
	global_load_dwordx4 v[74:77], v[16:17], off offset:336
	global_load_dwordx4 v[62:65], v[14:15], off offset:2384
	v_add_co_u32_e32 v14, vcc, 0x3000, v18
	s_lshl_b32 s3, s14, 1
	s_nop 0
	v_addc_co_u32_e32 v15, vcc, 0, v19, vcc
	global_load_dwordx4 v[66:69], v[18:19], off offset:2384
	global_load_dwordx4 v[78:81], v[14:15], off offset:336
	s_and_b32 s3, s3, -8
	s_lshl_b32 s9, s17, 1
	v_mov_b32_e32 v14, 0
	s_lshl_b32 s3, s17, 1
	s_lshl_b32 s5, s5, 10
	s_lshl_b32 s7, s16, 11
	s_or_b32 s9, s9, 1
	s_mov_b32 s17, -2
	v_mov_b32_e32 v15, v14
	v_mov_b32_e32 v16, v14
	v_mov_b32_e32 v17, v14
	v_mov_b32_e32 v18, v14
	v_mov_b32_e32 v19, v14
	v_mov_b32_e32 v20, v14
	v_mov_b32_e32 v21, v14
	v_mov_b32_e32 v22, v14
	v_mov_b32_e32 v23, v14
	v_mov_b32_e32 v24, v14
	v_mov_b32_e32 v25, v14
	s_waitcnt vmcnt(15)
	v_mov_b32_e32 v26, v14
	v_mov_b32_e32 v27, v14
	v_mov_b32_e32 v28, v14
	v_mov_b32_e32 v29, v14
	s_waitcnt vmcnt(14)
	v_mov_b32_e32 v30, v14
	v_mov_b32_e32 v31, v14
	v_mov_b32_e32 v32, v14
	v_mov_b32_e32 v33, v14
	v_mov_b32_e32 v38, v14
	v_mov_b32_e32 v39, v14
	v_mov_b32_e32 v40, v14
	v_mov_b32_e32 v41, v14
	s_waitcnt vmcnt(13)
	v_mov_b32_e32 v42, v14
	v_mov_b32_e32 v43, v14
	v_mov_b32_e32 v44, v14
	v_mov_b32_e32 v45, v14
	s_waitcnt vmcnt(12)
	v_mov_b32_e32 v46, v14
	v_mov_b32_e32 v47, v14
	v_mov_b32_e32 v48, v14
	v_mov_b32_e32 v49, v14
	s_waitcnt vmcnt(0)
.LBB0_855:
	s_add_i32 s10, s17, 4
	s_min_i32 s10, s10, s9
	s_lshl_b32 s18, s10, 1
	v_or_b32_e32 v0, s18, v106
	v_sub_u32_e32 v0, s2, v0
	v_cmp_lt_i32_e32 vcc, -1, v0
	v_mov_b32_e32 v108, 0
	v_mov_b32_e32 v109, 0
	v_mov_b32_e32 v110, 0
	v_mov_b32_e32 v111, 0
	s_and_saveexec_b64 s[10:11], vcc
	v_lshlrev_b64 v[108:109], 9, v[0:1]
	v_lshl_add_u64 v[108:109], v[102:103], 0, v[108:109]
	global_load_dwordx4 v[108:111], v[108:109], off
.Ls5x_857:
	s_or_b64 exec, exec, s[10:11]
	v_add_u32_e32 v118, 1, v0
	v_cmp_lt_i32_e32 vcc, -1, v118
	v_mov_b32_e32 v116, 0
	v_mov_b32_e32 v112, 0
	v_mov_b32_e32 v113, 0
	v_mov_b32_e32 v114, 0
	v_mov_b32_e32 v115, 0
	s_and_saveexec_b64 s[10:11], vcc
	v_mov_b32_e32 v119, v1
	v_lshlrev_b64 v[112:113], 9, v[118:119]
	v_lshl_add_u64 v[112:113], v[102:103], 0, v[112:113]
	global_load_dwordx4 v[112:115], v[112:113], off
.Ls5x_859:
	s_or_b64 exec, exec, s[10:11]
	v_add_u32_e32 v232, 2, v0
	v_cmp_lt_i32_e32 vcc, -1, v232
	v_mov_b32_e32 v117, 0
	v_mov_b32_e32 v118, 0
	v_mov_b32_e32 v119, 0
	s_and_saveexec_b64 s[10:11], vcc
	v_mov_b32_e32 v233, v1
	v_lshlrev_b64 v[116:117], 9, v[232:233]
	v_lshl_add_u64 v[116:117], v[102:103], 0, v[116:117]
	global_load_dwordx4 v[116:119], v[116:117], off
.Ls5x_861:
	s_or_b64 exec, exec, s[10:11]
	v_add_u32_e32 v0, 3, v0
	v_cmp_lt_i32_e32 vcc, -1, v0
	v_mov_b32_e32 v232, 0
	v_mov_b32_e32 v233, 0
	v_mov_b32_e32 v234, 0
	v_mov_b32_e32 v235, 0
	s_and_saveexec_b64 s[10:11], vcc
	v_lshlrev_b64 v[232:233], 9, v[0:1]
	v_lshl_add_u64 v[232:233], v[102:103], 0, v[232:233]
	global_load_dwordx4 v[232:235], v[232:233], off
; DI f32x4 mfma16(bf16x8 a, bf16x8 b, f32x4 c) { return __builtin_amdgcn_mfma_f32_16x16x32_bf16(a, b, c, 0, 0, 0); }
; template <int AT, int BT, class FA, class FB>
; DI void wgemm(f32x4 (&acc)[AT][BT], int ksteps, FA fa, FB fb) {
;     ...
;   for (int ks = 0; ks < ksteps; ++ks) {
;     bf16x8 a2[AT], b2[BT];
;     const int kn = (ks + 2 < ksteps) ? ks + 2 : ksteps - 1;
; #pragma unroll
;     for (int i = 0; i < AT; ++i) a2[i] = fa(i, kn);
; #pragma unroll
;     for (int j = 0; j < BT; ++j) b2[j] = fb(j, kn);
;     __builtin_amdgcn_sched_barrier(0);
; #pragma unroll
;     for (int i = 0; i < AT; ++i)
; #pragma unroll
;       for (int j = 0; j < BT; ++j) acc[i][j] = mfma16(a0[i], b0[j], acc[i][j]);
;     __builtin_amdgcn_sched_barrier(0);
; #pragma unroll
;     for (int i = 0; i < AT; ++i) { a0[i] = a1[i]; a1[i] = a2[i]; }
; #pragma unroll
;     for (int j = 0; j < BT; ++j) { b0[j] = b1[j]; b1[j] = b2[j]; }
;   }
; DI void s5_stage3_item(const Params& P, int l, int it, u16* hs, int wave, int lane) {
;     ...
;                 [&](int i, int ks) { const int j = 4 * jg + i, ii = 2 * ks + (q >> 1); const int d = j - ii;
;                                      return (d >= 0) ? ld8(Kt + ((size_t)d * 16 + jn) * 16 + (q & 1) * 8) : zf; },
;                 [&](int jt, int ks) { return ld8(up + ((size_t)(2 * th + jt) * 16 * 64 + 2 * ks) * DINP); });
.Ls5x_863:
	s_or_b64 exec, exec, s[10:11]
	s_ashr_i32 s19, s18, 31
	s_add_u32 s10, s7, s18
	s_addc_u32 s11, 0, s19
	s_mul_i32 s20, s11, 0x1400
	v_mad_u64_u32 v[82:83], s[10:11], s10, v133, v[90:91]
	s_add_u32 s10, s5, s18
	s_addc_u32 s11, 0, s19
	s_mul_i32 s18, s11, 0x1400
	v_mad_u64_u32 v[84:85], s[10:11], s10, v133, v[90:91]
	v_add_u32_e32 v83, s20, v83
	v_add_u32_e32 v85, s18, v85
	global_load_dwordx4 v[86:89], v[82:83], off offset:2384
	s_nop 0
	global_load_dwordx4 v[82:85], v[84:85], off offset:2384
	v_mfma_f32_16x16x32_bf16 v[46:49], v[6:9], v[66:69], v[46:49]
	v_mfma_f32_16x16x32_bf16 v[42:45], v[6:9], v[62:65], v[42:45]
	v_mfma_f32_16x16x32_bf16 v[38:41], v[34:37], v[66:69], v[38:41]
	v_mfma_f32_16x16x32_bf16 v[30:33], v[34:37], v[62:65], v[30:33]
	v_mfma_f32_16x16x32_bf16 v[26:29], v[54:57], v[66:69], v[26:29]
	v_mfma_f32_16x16x32_bf16 v[22:25], v[54:57], v[62:65], v[22:25]
	v_mfma_f32_16x16x32_bf16 v[18:21], v[58:61], v[66:69], v[18:21]
	v_mfma_f32_16x16x32_bf16 v[14:17], v[58:61], v[62:65], v[14:17]
	s_add_i32 s17, s17, 1
	s_cmp_lg_u32 s3, s17
	s_cbranch_scc0 .Ls5x_exit
	s_waitcnt vmcnt(6)
	v_mov_b64_e32 v[66:67], v[78:79]
	v_mov_b64_e32 v[62:63], v[74:75]
	v_mov_b64_e32 v[68:69], v[80:81]
	v_mov_b64_e32 v[64:65], v[76:77]
	v_mov_b64_e32 v[6:7], v[2:3]
	v_mov_b64_e32 v[8:9], v[4:5]
	v_mov_b64_e32 v[34:35], v[10:11]
	v_mov_b64_e32 v[36:37], v[12:13]
	v_mov_b64_e32 v[54:55], v[50:51]
	v_mov_b64_e32 v[56:57], v[52:53]
	v_mov_b64_e32 v[58:59], v[70:71]
	v_mov_b64_e32 v[60:61], v[72:73]
	s_add_i32 s10, s17, 4
	s_min_i32 s10, s10, s9
	s_lshl_b32 s18, s10, 1
	v_or_b32_e32 v0, s18, v106
	v_sub_u32_e32 v0, s2, v0
	v_cmp_lt_i32_e32 vcc, -1, v0
	v_mov_b32_e32 v2, 0
	v_mov_b32_e32 v3, 0
	v_mov_b32_e32 v4, 0
	v_mov_b32_e32 v5, 0
	s_and_saveexec_b64 s[10:11], vcc
	v_lshlrev_b64 v[2:3], 9, v[0:1]
	v_lshl_add_u64 v[2:3], v[102:103], 0, v[2:3]
	global_load_dwordx4 v[2:5], v[2:3], off
.LBB0_857:
	s_or_b64 exec, exec, s[10:11]
	v_add_u32_e32 v52, 1, v0
	v_cmp_lt_i32_e32 vcc, -1, v52
	v_mov_b32_e32 v50, 0
	v_mov_b32_e32 v10, 0
	v_mov_b32_e32 v11, 0
	v_mov_b32_e32 v12, 0
	v_mov_b32_e32 v13, 0
	s_and_saveexec_b64 s[10:11], vcc
	v_mov_b32_e32 v53, v1
	v_lshlrev_b64 v[10:11], 9, v[52:53]
	v_lshl_add_u64 v[10:11], v[102:103], 0, v[10:11]
	global_load_dwordx4 v[10:13], v[10:11], off
.LBB0_859:
	s_or_b64 exec, exec, s[10:11]
	v_add_u32_e32 v70, 2, v0
	v_cmp_lt_i32_e32 vcc, -1, v70
	v_mov_b32_e32 v51, 0
	v_mov_b32_e32 v52, 0
	v_mov_b32_e32 v53, 0
	s_and_saveexec_b64 s[10:11], vcc
	v_mov_b32_e32 v71, v1
	v_lshlrev_b64 v[50:51], 9, v[70:71]
	v_lshl_add_u64 v[50:51], v[102:103], 0, v[50:51]
	global_load_dwordx4 v[50:53], v[50:51], off
.LBB0_861:
	s_or_b64 exec, exec, s[10:11]
	v_add_u32_e32 v0, 3, v0
	v_cmp_lt_i32_e32 vcc, -1, v0
	v_mov_b32_e32 v70, 0
	v_mov_b32_e32 v71, 0
	v_mov_b32_e32 v72, 0
	v_mov_b32_e32 v73, 0
	s_and_saveexec_b64 s[10:11], vcc
	v_lshlrev_b64 v[70:71], 9, v[0:1]
	v_lshl_add_u64 v[70:71], v[102:103], 0, v[70:71]
	global_load_dwordx4 v[70:73], v[70:71], off
.LBB0_863:
	s_or_b64 exec, exec, s[10:11]
	s_ashr_i32 s19, s18, 31
	s_add_u32 s10, s7, s18
	s_addc_u32 s11, 0, s19
	s_mul_i32 s20, s11, 0x1400
	v_mad_u64_u32 v[74:75], s[10:11], s10, v133, v[90:91]
	s_add_u32 s10, s5, s18
	s_addc_u32 s11, 0, s19
	s_mul_i32 s18, s11, 0x1400
	v_mad_u64_u32 v[76:77], s[10:11], s10, v133, v[90:91]
	v_add_u32_e32 v75, s20, v75
	v_add_u32_e32 v77, s18, v77
	global_load_dwordx4 v[78:81], v[74:75], off offset:2384
	s_nop 0
	global_load_dwordx4 v[74:77], v[76:77], off offset:2384
	v_mfma_f32_16x16x32_bf16 v[46:49], v[6:9], v[66:69], v[46:49]
	v_mfma_f32_16x16x32_bf16 v[42:45], v[6:9], v[62:65], v[42:45]
	v_mfma_f32_16x16x32_bf16 v[38:41], v[34:37], v[66:69], v[38:41]
	v_mfma_f32_16x16x32_bf16 v[30:33], v[34:37], v[62:65], v[30:33]
	v_mfma_f32_16x16x32_bf16 v[26:29], v[54:57], v[66:69], v[26:29]
	v_mfma_f32_16x16x32_bf16 v[22:25], v[54:57], v[62:65], v[22:25]
	v_mfma_f32_16x16x32_bf16 v[18:21], v[58:61], v[66:69], v[18:21]
	v_mfma_f32_16x16x32_bf16 v[14:17], v[58:61], v[62:65], v[14:17]
	s_add_i32 s17, s17, 1
	s_cmp_lg_u32 s3, s17
	s_cbranch_scc0 .Ls5x_exit
	s_waitcnt vmcnt(6)
	v_mov_b64_e32 v[66:67], v[86:87]
	v_mov_b64_e32 v[62:63], v[82:83]
	v_mov_b64_e32 v[68:69], v[88:89]
	v_mov_b64_e32 v[64:65], v[84:85]
	v_mov_b64_e32 v[6:7], v[108:109]
	v_mov_b64_e32 v[8:9], v[110:111]
	v_mov_b64_e32 v[34:35], v[112:113]
	v_mov_b64_e32 v[36:37], v[114:115]
	v_mov_b64_e32 v[54:55], v[116:117]
	v_mov_b64_e32 v[56:57], v[118:119]
	v_mov_b64_e32 v[58:59], v[232:233]
	v_mov_b64_e32 v[60:61], v[234:235]
	s_branch .LBB0_855
.Ls5x_exit:
	s_waitcnt vmcnt(0)
	s_branch .LBB0_836
